# MFMA order in each 16-block: same-accumulator k0,k1 pairs back-to-back (SrcC forwarding), plus x->f16 loop with 16 loads in flight
# speedup vs baseline: 1.0024x; 1.0024x over previous
; #define PG8_STAGE(bufoff, gbase, voff) do { _Pragma("unroll") for (int _i = 0; _i < 2; ++_i) \
;         __builtin_amdgcn_global_load_lds((const unsigned*)((const char*)(gbase) + (voff)[_i]), (PG8_LAS unsigned*)(lds + (bufoff) + ldsw + _i * 8192), 16, 0, 0); } while (0)
; #define PG8_LDA(dst, b, h) do { _Pragma("unroll") for (int m = 0; m < 4; ++m) _Pragma("unroll") for (int k = 0; k < 2; ++k) dst[m][k] = *(const PG8_LAS bf16x8*)(lds + PG8_SA(b, h) + aoff + m * 2048 + k * 1024); } while (0)
; #define PG8_LDB(dst, b, h) do { _Pragma("unroll") for (int n = 0; n < 2; ++n) _Pragma("unroll") for (int k = 0; k < 2; ++k) dst[n][k] = *(const PG8_LAS bf16x8*)(lds + PG8_SB(b, h) + boff + n * 2048 + k * 1024); } while (0)
; #define PG8_MMA(ai, bj, At, Bt) do { __builtin_amdgcn_s_setprio(1); _Pragma("unroll") for (int m = 0; m < 4; ++m) _Pragma("unroll") for (int n = 0; n < 2; ++n) _Pragma("unroll") for (int k = 0; k < 2; ++k) \
;         acc[ai][bj][m][n] = mma16<Epi::F16>(Bt[n][k], At[m][k], acc[ai][bj][m][n]); __builtin_amdgcn_s_setprio(0); } while (0)
; #define PG8_WAIT_V(n) asm volatile("s_waitcnt vmcnt(" #n ")" ::: "memory")
; #define PG8_WAIT_L(n) asm volatile("s_waitcnt lgkmcnt(" #n ")" ::: "memory")
; #define PG8_BAR __builtin_amdgcn_s_barrier()
; #define PG8_SCHED __builtin_amdgcn_sched_barrier(0)
; template <class Epi, class Sched, bool ALIGN_EPI = false, bool SP2 = false>
; __device__ __forceinline__ void gemm_phase(PG8_LAS unsigned char* lds, const Gemm g, const Sched& S, const Epi& E) {
;     ...
;             PG8_LDB(B0, 0, 0); PG8_LDB(B1, 0, 1); PG8_SCHED; PG8_LDA(At, 0, 0); PG8_STAGE(PG8_SA(1, 1), a1 + hstep, voffA);
;             PG8_WAIT_V(8); PG8_WAIT_L(0); PG8_BAR; PG8_MMA(0, 0, At, B0); PG8_MMA(0, 1, At, B1); PG8_BAR; PG8_SCHED;
;             PG8_LDA(At, 0, 1); PG8_STAGE(PG8_SB(0, 0), b2, voffB); PG8_STAGE(PG8_SB(0, 1), b2 + hstep, voffB); PG8_STAGE(PG8_SA(0, 0), a2, voffA);
.LBB0_92:
	s_add_u32 s10, s8, 0xfffc0080
	s_addc_u32 s11, s9, -1
	s_add_i32 s14, 0, 0x10000
	s_cmp_eq_u32 vcc_lo, 12
	s_cselect_b32 s65, s35, s11
	s_cselect_b32 s64, s96, s10
	v_add_u32_e32 v102, s14, v185
	s_cselect_b32 s11, s31, s99
	s_cselect_b32 s10, s97, s98
	s_add_i32 vcc_hi, 0, 0x14000
	ds_read_b128 v[128:131], v102
	ds_read_b128 v[132:135], v102 offset:1024
	ds_read_b128 v[136:139], v102 offset:2048
	ds_read_b128 v[140:143], v102 offset:3072
	v_add_u32_e32 v102, vcc_hi, v185
	ds_read_b128 v[144:147], v102
	ds_read_b128 v[148:151], v102 offset:1024
	ds_read_b128 v[152:155], v102 offset:2048
	ds_read_b128 v[156:159], v102 offset:3072
	v_lshl_add_u64 v[102:103], s[8:9], 0, v[198:199]
	s_add_i32 m0, s52, 0xc000
	ds_read_b128 v[168:171], v209
	ds_read_b128 v[172:175], v209 offset:1024
	ds_read_b128 v[176:179], v209 offset:2048
	ds_read_b128 v[180:183], v209 offset:3072
	ds_read_b128 v[212:215], v209 offset:4096
	ds_read_b128 v[216:219], v209 offset:5120
	ds_read_b128 v[220:223], v209 offset:6144
	ds_read_b128 v[224:227], v209 offset:7168
	global_load_lds_dwordx4 v[102:103], off
	v_lshl_add_u64 v[102:103], s[8:9], 0, v[200:201]
	s_add_i32 m0, s52, 0xe000
	s_nop 0
	global_load_lds_dwordx4 v[102:103], off
	s_waitcnt vmcnt(8)
	s_waitcnt lgkmcnt(0)
	s_barrier
	s_setprio 1
	s_waitcnt lgkmcnt(0)
	v_mfma_f32_16x16x32_f16 v[164:167], v[128:131], v[168:171], v[164:167]
	v_mfma_f32_16x16x32_f16 v[164:167], v[132:135], v[172:175], v[164:167]
	v_mfma_f32_16x16x32_f16 v[62:65], v[136:139], v[168:171], v[62:65]
	v_mfma_f32_16x16x32_f16 v[62:65], v[140:143], v[172:175], v[62:65]
	v_mfma_f32_16x16x32_f16 v[124:127], v[128:131], v[176:179], v[124:127]
	v_mfma_f32_16x16x32_f16 v[124:127], v[132:135], v[180:183], v[124:127]
	v_mfma_f32_16x16x32_f16 v[54:57], v[136:139], v[176:179], v[54:57]
	v_mfma_f32_16x16x32_f16 v[54:57], v[140:143], v[180:183], v[54:57]
	v_mfma_f32_16x16x32_f16 v[114:117], v[128:131], v[212:215], v[114:117]
	v_mfma_f32_16x16x32_f16 v[114:117], v[132:135], v[216:219], v[114:117]
	v_mfma_f32_16x16x32_f16 v[44:47], v[136:139], v[212:215], v[44:47]
	v_mfma_f32_16x16x32_f16 v[44:47], v[140:143], v[216:219], v[44:47]
	v_mfma_f32_16x16x32_f16 v[108:111], v[128:131], v[220:223], v[110:113]
	v_mfma_f32_16x16x32_f16 v[108:111], v[132:135], v[224:227], v[108:111]
	v_mfma_f32_16x16x32_f16 v[40:43], v[136:139], v[220:223], v[40:43]
	v_mfma_f32_16x16x32_f16 v[40:43], v[140:143], v[224:227], v[40:43]
	s_setprio 0
	s_setprio 1
	v_mfma_f32_16x16x32_f16 v[160:163], v[144:147], v[168:171], v[160:163]
	v_mfma_f32_16x16x32_f16 v[160:163], v[148:151], v[172:175], v[160:163]
	v_mfma_f32_16x16x32_f16 v[58:61], v[152:155], v[168:171], v[58:61]
	v_mfma_f32_16x16x32_f16 v[58:61], v[156:159], v[172:175], v[58:61]
	v_mfma_f32_16x16x32_f16 v[118:121], v[144:147], v[176:179], v[120:123]
	v_mfma_f32_16x16x32_f16 v[118:121], v[148:151], v[180:183], v[118:121]
	v_mfma_f32_16x16x32_f16 v[50:53], v[152:155], v[176:179], v[50:53]
	v_mfma_f32_16x16x32_f16 v[50:53], v[156:159], v[180:183], v[50:53]
	v_mfma_f32_16x16x32_f16 v[102:105], v[144:147], v[212:215], v[104:107]
	v_mfma_f32_16x16x32_f16 v[102:105], v[148:151], v[216:219], v[102:105]
	v_mfma_f32_16x16x32_f16 v[36:39], v[152:155], v[212:215], v[36:39]
	v_mfma_f32_16x16x32_f16 v[36:39], v[156:159], v[216:219], v[36:39]
	v_mfma_f32_16x16x32_f16 v[98:101], v[144:147], v[220:223], v[98:101]
	v_mfma_f32_16x16x32_f16 v[98:101], v[148:151], v[224:227], v[98:101]
	v_mfma_f32_16x16x32_f16 v[32:35], v[152:155], v[220:223], v[32:35]
	v_mfma_f32_16x16x32_f16 v[32:35], v[156:159], v[224:227], v[32:35]
	s_setprio 0
	s_barrier
	s_add_i32 s14, s14, s44
	v_lshl_add_u64 v[228:229], s[10:11], 0, v[188:189]
	s_mov_b32 m0, s14
	ds_read_b128 v[168:171], v209 offset:16384
	ds_read_b128 v[172:175], v209 offset:17408
	ds_read_b128 v[176:179], v209 offset:18432
	ds_read_b128 v[180:183], v209 offset:19456
	ds_read_b128 v[212:215], v209 offset:20480
	ds_read_b128 v[216:219], v209 offset:21504
	ds_read_b128 v[220:223], v209 offset:22528
	ds_read_b128 v[224:227], v209 offset:23552
	global_load_lds_dwordx4 v[228:229], off
	s_add_i32 m0, s14, 0x2000
	s_add_u32 s14, s10, 0x40000
	v_lshl_add_u64 v[230:231], s[10:11], 0, v[192:193]
	s_addc_u32 s15, s11, 0
	s_add_i32 vcc_hi, vcc_hi, s44
	global_load_lds_dwordx4 v[230:231], off
	v_lshl_add_u64 v[106:107], s[14:15], 0, v[188:189]
	s_mov_b32 m0, vcc_hi
	v_lshl_add_u64 v[232:233], s[64:65], 0, v[186:187]
	global_load_lds_dwordx4 v[106:107], off
	v_lshl_add_u64 v[106:107], s[14:15], 0, v[192:193]
	s_add_i32 m0, vcc_hi, 0x2000
	v_lshl_add_u64 v[234:235], s[64:65], 0, v[190:191]
	global_load_lds_dwordx4 v[106:107], off
	s_mov_b32 m0, s52
	s_nop 0
	global_load_lds_dwordx4 v[232:233], off
	s_mov_b32 m0, s53
	s_nop 0
	global_load_lds_dwordx4 v[234:235], off
	s_waitcnt vmcnt(8)
	s_waitcnt lgkmcnt(0)
	s_barrier
; #define PG8_STAGE(bufoff, gbase, voff) do { _Pragma("unroll") for (int _i = 0; _i < 2; ++_i) \
;         __builtin_amdgcn_global_load_lds((const unsigned*)((const char*)(gbase) + (voff)[_i]), (PG8_LAS unsigned*)(lds + (bufoff) + ldsw + _i * 8192), 16, 0, 0); } while (0)
; #define PG8_LDA(dst, b, h) do { _Pragma("unroll") for (int m = 0; m < 4; ++m) _Pragma("unroll") for (int k = 0; k < 2; ++k) dst[m][k] = *(const PG8_LAS bf16x8*)(lds + PG8_SA(b, h) + aoff + m * 2048 + k * 1024); } while (0)
; #define PG8_LDB(dst, b, h) do { _Pragma("unroll") for (int n = 0; n < 2; ++n) _Pragma("unroll") for (int k = 0; k < 2; ++k) dst[n][k] = *(const PG8_LAS bf16x8*)(lds + PG8_SB(b, h) + boff + n * 2048 + k * 1024); } while (0)
; #define PG8_MMA(ai, bj, At, Bt) do { __builtin_amdgcn_s_setprio(1); _Pragma("unroll") for (int m = 0; m < 4; ++m) _Pragma("unroll") for (int n = 0; n < 2; ++n) _Pragma("unroll") for (int k = 0; k < 2; ++k) \
;         acc[ai][bj][m][n] = mma16<Epi::F16>(Bt[n][k], At[m][k], acc[ai][bj][m][n]); __builtin_amdgcn_s_setprio(0); } while (0)
; #define PG8_WAIT_V(n) asm volatile("s_waitcnt vmcnt(" #n ")" ::: "memory")
; #define PG8_WAIT_L(n) asm volatile("s_waitcnt lgkmcnt(" #n ")" ::: "memory")
; #define PG8_BAR __builtin_amdgcn_s_barrier()
; #define PG8_SCHED __builtin_amdgcn_sched_barrier(0)
; template <class Epi, class Sched, bool ALIGN_EPI = false, bool SP2 = false>
; __device__ __forceinline__ void gemm_phase(PG8_LAS unsigned char* lds, const Gemm g, const Sched& S, const Epi& E) {
;     ...
;             PG8_WAIT_V(8); PG8_WAIT_L(0); PG8_BAR; PG8_MMA(1, 0, At, B0); PG8_MMA(1, 1, At, B1); PG8_BAR; PG8_SCHED;
;             PG8_LDB(B0, 1, 0); PG8_LDB(B1, 1, 1); PG8_SCHED; PG8_LDA(At, 1, 0); PG8_STAGE(PG8_SA(0, 1), a2 + hstep, voffA);
;             PG8_WAIT_V(8); PG8_WAIT_L(0); PG8_BAR; PG8_MMA(0, 0, At, B0); PG8_MMA(0, 1, At, B1); PG8_BAR; PG8_SCHED;
	s_setprio 1
	s_waitcnt lgkmcnt(0)
	v_mfma_f32_16x16x32_f16 v[94:97], v[128:131], v[168:171], v[94:97]
	v_mfma_f32_16x16x32_f16 v[94:97], v[132:135], v[172:175], v[94:97]
	v_mfma_f32_16x16x32_f16 v[28:31], v[136:139], v[168:171], v[28:31]
	v_mfma_f32_16x16x32_f16 v[28:31], v[140:143], v[172:175], v[28:31]
	v_mfma_f32_16x16x32_f16 v[86:89], v[128:131], v[176:179], v[86:89]
	v_mfma_f32_16x16x32_f16 v[86:89], v[132:135], v[180:183], v[86:89]
	v_mfma_f32_16x16x32_f16 v[20:23], v[136:139], v[176:179], v[20:23]
	v_mfma_f32_16x16x32_f16 v[20:23], v[140:143], v[180:183], v[20:23]
	v_mfma_f32_16x16x32_f16 v[78:81], v[128:131], v[212:215], v[78:81]
	v_mfma_f32_16x16x32_f16 v[78:81], v[132:135], v[216:219], v[78:81]
	v_mfma_f32_16x16x32_f16 v[12:15], v[136:139], v[212:215], v[12:15]
	v_mfma_f32_16x16x32_f16 v[12:15], v[140:143], v[216:219], v[12:15]
	v_mfma_f32_16x16x32_f16 v[74:77], v[128:131], v[220:223], v[74:77]
	v_mfma_f32_16x16x32_f16 v[74:77], v[132:135], v[224:227], v[74:77]
	v_mfma_f32_16x16x32_f16 v[8:11], v[136:139], v[220:223], v[8:11]
	v_mfma_f32_16x16x32_f16 v[8:11], v[140:143], v[224:227], v[8:11]
	s_setprio 0
	s_setprio 1
	v_mfma_f32_16x16x32_f16 v[90:93], v[144:147], v[168:171], v[90:93]
	v_mfma_f32_16x16x32_f16 v[90:93], v[148:151], v[172:175], v[90:93]
	v_mfma_f32_16x16x32_f16 v[24:27], v[152:155], v[168:171], v[24:27]
	v_mfma_f32_16x16x32_f16 v[24:27], v[156:159], v[172:175], v[24:27]
	v_mfma_f32_16x16x32_f16 v[82:85], v[144:147], v[176:179], v[82:85]
	v_mfma_f32_16x16x32_f16 v[82:85], v[148:151], v[180:183], v[82:85]
	v_mfma_f32_16x16x32_f16 v[16:19], v[152:155], v[176:179], v[16:19]
	v_mfma_f32_16x16x32_f16 v[16:19], v[156:159], v[180:183], v[16:19]
	v_mfma_f32_16x16x32_f16 v[70:73], v[144:147], v[212:215], v[70:73]
	v_mfma_f32_16x16x32_f16 v[70:73], v[148:151], v[216:219], v[70:73]
	v_mfma_f32_16x16x32_f16 v[4:7], v[152:155], v[212:215], v[4:7]
	v_mfma_f32_16x16x32_f16 v[4:7], v[156:159], v[216:219], v[4:7]
	v_mfma_f32_16x16x32_f16 v[66:69], v[144:147], v[220:223], v[66:69]
	v_mfma_f32_16x16x32_f16 v[66:69], v[148:151], v[224:227], v[66:69]
	v_mfma_f32_16x16x32_f16 v[0:3], v[152:155], v[220:223], v[0:3]
	v_mfma_f32_16x16x32_f16 v[0:3], v[156:159], v[224:227], v[0:3]
	s_setprio 0
	s_barrier
	s_add_i32 vcc_hi, 0, 0x18000
	v_add_u32_e32 v106, vcc_hi, v185
	s_add_i32 s51, 0, 0x1c000
	ds_read_b128 v[128:131], v106
	ds_read_b128 v[132:135], v106 offset:1024
	ds_read_b128 v[136:139], v106 offset:2048
	ds_read_b128 v[140:143], v106 offset:3072
	v_add_u32_e32 v106, s51, v185
	ds_read_b128 v[144:147], v106
	ds_read_b128 v[148:151], v106 offset:1024
	ds_read_b128 v[152:155], v106 offset:2048
	ds_read_b128 v[156:159], v106 offset:3072
	s_add_u32 s14, s64, 0x40000
	s_addc_u32 s15, s65, 0
	s_mov_b32 m0, s59
	v_lshl_add_u64 v[106:107], s[14:15], 0, v[186:187]
	ds_read_b128 v[168:171], v209 offset:32768
	ds_read_b128 v[172:175], v209 offset:33792
	ds_read_b128 v[176:179], v209 offset:34816
	ds_read_b128 v[180:183], v209 offset:35840
	ds_read_b128 v[212:215], v209 offset:36864
	ds_read_b128 v[216:219], v209 offset:37888
	ds_read_b128 v[220:223], v209 offset:38912
	ds_read_b128 v[224:227], v209 offset:39936
	global_load_lds_dwordx4 v[106:107], off
	v_lshl_add_u64 v[106:107], s[14:15], 0, v[190:191]
	s_mov_b32 m0, s60
	s_nop 0
	global_load_lds_dwordx4 v[106:107], off
	s_waitcnt vmcnt(8)
	s_waitcnt lgkmcnt(0)
	s_barrier
	s_setprio 1
	s_waitcnt lgkmcnt(0)
	v_mfma_f32_16x16x32_f16 v[164:167], v[128:131], v[168:171], v[164:167]
	v_mfma_f32_16x16x32_f16 v[62:65], v[136:139], v[168:171], v[62:65]
	v_mfma_f32_16x16x32_f16 v[122:125], v[128:131], v[176:179], v[124:127]
	v_mfma_f32_16x16x32_f16 v[54:57], v[136:139], v[176:179], v[54:57]
	v_mfma_f32_16x16x32_f16 v[112:115], v[128:131], v[212:215], v[114:117]
	v_mfma_f32_16x16x32_f16 v[44:47], v[136:139], v[212:215], v[44:47]
	v_mfma_f32_16x16x32_f16 v[106:109], v[128:131], v[220:223], v[108:111]
	v_mfma_f32_16x16x32_f16 v[40:43], v[136:139], v[220:223], v[40:43]
	v_mfma_f32_16x16x32_f16 v[164:167], v[132:135], v[172:175], v[164:167]
	v_mfma_f32_16x16x32_f16 v[62:65], v[140:143], v[172:175], v[62:65]
	v_mfma_f32_16x16x32_f16 v[124:127], v[132:135], v[180:183], v[122:125]
	v_mfma_f32_16x16x32_f16 v[54:57], v[140:143], v[180:183], v[54:57]
	v_mfma_f32_16x16x32_f16 v[114:117], v[132:135], v[216:219], v[112:115]
	v_mfma_f32_16x16x32_f16 v[44:47], v[140:143], v[216:219], v[44:47]
	v_mfma_f32_16x16x32_f16 v[110:113], v[132:135], v[224:227], v[106:109]
	v_mfma_f32_16x16x32_f16 v[40:43], v[140:143], v[224:227], v[40:43]
	s_setprio 0
	s_setprio 1
	v_mfma_f32_16x16x32_f16 v[106:109], v[144:147], v[168:171], v[160:163]
	v_mfma_f32_16x16x32_f16 v[160:163], v[148:151], v[172:175], v[106:109]
	v_mfma_f32_16x16x32_f16 v[58:61], v[152:155], v[168:171], v[58:61]
	v_mfma_f32_16x16x32_f16 v[106:109], v[144:147], v[176:179], v[118:121]
	v_mfma_f32_16x16x32_f16 v[50:53], v[152:155], v[176:179], v[50:53]
	v_mfma_f32_16x16x32_f16 v[102:105], v[144:147], v[212:215], v[102:105]
	v_mfma_f32_16x16x32_f16 v[36:39], v[152:155], v[212:215], v[36:39]
	v_mfma_f32_16x16x32_f16 v[98:101], v[144:147], v[220:223], v[98:101]
	v_mfma_f32_16x16x32_f16 v[32:35], v[152:155], v[220:223], v[32:35]
	v_mfma_f32_16x16x32_f16 v[58:61], v[156:159], v[172:175], v[58:61]
	v_mfma_f32_16x16x32_f16 v[120:123], v[148:151], v[180:183], v[106:109]
	v_mfma_f32_16x16x32_f16 v[50:53], v[156:159], v[180:183], v[50:53]
	v_mfma_f32_16x16x32_f16 v[104:107], v[148:151], v[216:219], v[102:105]
	v_mfma_f32_16x16x32_f16 v[36:39], v[156:159], v[216:219], v[36:39]
	v_mfma_f32_16x16x32_f16 v[98:101], v[148:151], v[224:227], v[98:101]
	v_mfma_f32_16x16x32_f16 v[32:35], v[156:159], v[224:227], v[32:35]
	s_setprio 0
	s_barrier
; #define PG8_STAGE(bufoff, gbase, voff) do { _Pragma("unroll") for (int _i = 0; _i < 2; ++_i) \
;         __builtin_amdgcn_global_load_lds((const unsigned*)((const char*)(gbase) + (voff)[_i]), (PG8_LAS unsigned*)(lds + (bufoff) + ldsw + _i * 8192), 16, 0, 0); } while (0)
; #define PG8_LDA(dst, b, h) do { _Pragma("unroll") for (int m = 0; m < 4; ++m) _Pragma("unroll") for (int k = 0; k < 2; ++k) dst[m][k] = *(const PG8_LAS bf16x8*)(lds + PG8_SA(b, h) + aoff + m * 2048 + k * 1024); } while (0)
; #define PG8_MMA(ai, bj, At, Bt) do { __builtin_amdgcn_s_setprio(1); _Pragma("unroll") for (int m = 0; m < 4; ++m) _Pragma("unroll") for (int n = 0; n < 2; ++n) _Pragma("unroll") for (int k = 0; k < 2; ++k) \
;         acc[ai][bj][m][n] = mma16<Epi::F16>(Bt[n][k], At[m][k], acc[ai][bj][m][n]); __builtin_amdgcn_s_setprio(0); } while (0)
; #define PG8_WAIT_V(n) asm volatile("s_waitcnt vmcnt(" #n ")" ::: "memory")
; #define PG8_WAIT_L(n) asm volatile("s_waitcnt lgkmcnt(" #n ")" ::: "memory")
; #define PG8_BAR __builtin_amdgcn_s_barrier()
; #define PG8_SCHED __builtin_amdgcn_sched_barrier(0)
; template <class Epi, class Sched, bool ALIGN_EPI = false, bool SP2 = false>
; __device__ __forceinline__ void gemm_phase(PG8_LAS unsigned char* lds, const Gemm g, const Sched& S, const Epi& E) {
;     ...
;             PG8_LDA(At, 1, 1); PG8_STAGE(PG8_SB(1, 0), b3, voffB); PG8_STAGE(PG8_SB(1, 1), b3 + hstep, voffB); PG8_STAGE(PG8_SA(1, 0), a3, voffA);
;             PG8_WAIT_V(8); PG8_WAIT_L(0); PG8_BAR; PG8_MMA(1, 0, At, B0); PG8_MMA(1, 1, At, B1); PG8_BAR; PG8_SCHED;
	s_add_i32 s14, vcc_hi, s44
	v_lshl_add_u64 v[102:103], v[228:229], 0, s[88:89]
	s_mov_b32 m0, s14
	ds_read_b128 v[168:171], v209 offset:49152
	ds_read_b128 v[172:175], v209 offset:50176
	ds_read_b128 v[176:179], v209 offset:51200
	ds_read_b128 v[180:183], v209 offset:52224
	ds_read_b128 v[212:215], v209 offset:53248
	ds_read_b128 v[216:219], v209 offset:54272
	ds_read_b128 v[220:223], v209 offset:55296
	ds_read_b128 v[224:227], v209 offset:56320
	global_load_lds_dwordx4 v[102:103], off
	s_add_i32 m0, s14, 0x2000
	s_add_u32 s10, s10, 0x40080
	v_lshl_add_u64 v[102:103], v[230:231], 0, s[88:89]
	s_addc_u32 s11, s11, 0
	s_add_i32 s14, s51, s44
	global_load_lds_dwordx4 v[102:103], off
	v_lshl_add_u64 v[102:103], s[10:11], 0, v[188:189]
	s_mov_b32 m0, s14
	s_nop 0
	global_load_lds_dwordx4 v[102:103], off
	v_lshl_add_u64 v[102:103], s[10:11], 0, v[192:193]
	s_add_i32 m0, s14, 0x2000
	s_nop 0
	global_load_lds_dwordx4 v[102:103], off
	v_lshl_add_u64 v[102:103], v[232:233], 0, s[88:89]
	s_mov_b32 m0, s61
	s_nop 0
	global_load_lds_dwordx4 v[102:103], off
	v_lshl_add_u64 v[102:103], v[234:235], 0, s[88:89]
	s_mov_b32 m0, s63
	s_nop 0
	global_load_lds_dwordx4 v[102:103], off
	s_waitcnt vmcnt(8)
	s_waitcnt lgkmcnt(0)
	s_barrier
	s_setprio 1
	s_waitcnt lgkmcnt(0)
	v_mfma_f32_16x16x32_f16 v[94:97], v[128:131], v[168:171], v[94:97]
	v_mfma_f32_16x16x32_f16 v[94:97], v[132:135], v[172:175], v[94:97]
	v_mfma_f32_16x16x32_f16 v[28:31], v[136:139], v[168:171], v[28:31]
	v_mfma_f32_16x16x32_f16 v[28:31], v[140:143], v[172:175], v[28:31]
	v_mfma_f32_16x16x32_f16 v[86:89], v[128:131], v[176:179], v[86:89]
	v_mfma_f32_16x16x32_f16 v[86:89], v[132:135], v[180:183], v[86:89]
	v_mfma_f32_16x16x32_f16 v[20:23], v[136:139], v[176:179], v[20:23]
	v_mfma_f32_16x16x32_f16 v[20:23], v[140:143], v[180:183], v[20:23]
	v_mfma_f32_16x16x32_f16 v[78:81], v[128:131], v[212:215], v[78:81]
	v_mfma_f32_16x16x32_f16 v[78:81], v[132:135], v[216:219], v[78:81]
	v_mfma_f32_16x16x32_f16 v[12:15], v[136:139], v[212:215], v[12:15]
	v_mfma_f32_16x16x32_f16 v[12:15], v[140:143], v[216:219], v[12:15]
	v_mfma_f32_16x16x32_f16 v[74:77], v[128:131], v[220:223], v[74:77]
	v_mfma_f32_16x16x32_f16 v[74:77], v[132:135], v[224:227], v[74:77]
	v_mfma_f32_16x16x32_f16 v[8:11], v[136:139], v[220:223], v[8:11]
	v_mfma_f32_16x16x32_f16 v[8:11], v[140:143], v[224:227], v[8:11]
	s_setprio 0
	s_setprio 1
	v_mfma_f32_16x16x32_f16 v[90:93], v[144:147], v[168:171], v[90:93]
	v_mfma_f32_16x16x32_f16 v[90:93], v[148:151], v[172:175], v[90:93]
	v_mfma_f32_16x16x32_f16 v[24:27], v[152:155], v[168:171], v[24:27]
	v_mfma_f32_16x16x32_f16 v[24:27], v[156:159], v[172:175], v[24:27]
	v_mfma_f32_16x16x32_f16 v[82:85], v[144:147], v[176:179], v[82:85]
	v_mfma_f32_16x16x32_f16 v[82:85], v[148:151], v[180:183], v[82:85]
	v_mfma_f32_16x16x32_f16 v[16:19], v[152:155], v[176:179], v[16:19]
	v_mfma_f32_16x16x32_f16 v[16:19], v[156:159], v[180:183], v[16:19]
	v_mfma_f32_16x16x32_f16 v[70:73], v[144:147], v[212:215], v[70:73]
	v_mfma_f32_16x16x32_f16 v[70:73], v[148:151], v[216:219], v[70:73]
	v_mfma_f32_16x16x32_f16 v[4:7], v[152:155], v[212:215], v[4:7]
	v_mfma_f32_16x16x32_f16 v[4:7], v[156:159], v[216:219], v[4:7]
	v_mfma_f32_16x16x32_f16 v[66:69], v[144:147], v[220:223], v[66:69]
	v_mfma_f32_16x16x32_f16 v[66:69], v[148:151], v[224:227], v[66:69]
	v_mfma_f32_16x16x32_f16 v[0:3], v[152:155], v[220:223], v[0:3]
	v_mfma_f32_16x16x32_f16 v[0:3], v[156:159], v[224:227], v[0:3]
	s_setprio 0
	s_barrier
	s_add_i32 vcc_lo, vcc_lo, 2
	s_add_u32 s8, s8, 0x100
	s_addc_u32 s9, s9, 0
	s_add_u32 s98, s98, 0x100
	s_addc_u32 s99, s99, 0
	s_cmp_gt_u32 vcc_lo, 13
	s_cbranch_scc0 .LBB0_92
	s_and_b64 vcc, exec, s[20:21]
	s_cbranch_vccz .LBB0_95
	s_barrier

; #define PG8_STAGE(bufoff, gbase, voff) do { _Pragma("unroll") for (int _i = 0; _i < 2; ++_i) \
;         __builtin_amdgcn_global_load_lds((const unsigned*)((const char*)(gbase) + (voff)[_i]), (PG8_LAS unsigned*)(lds + (bufoff) + ldsw + _i * 8192), 16, 0, 0); } while (0)
; #define PG8_LDA(dst, b, h) do { _Pragma("unroll") for (int m = 0; m < 4; ++m) _Pragma("unroll") for (int k = 0; k < 2; ++k) dst[m][k] = *(const PG8_LAS bf16x8*)(lds + PG8_SA(b, h) + aoff + m * 2048 + k * 1024); } while (0)
; #define PG8_LDB(dst, b, h) do { _Pragma("unroll") for (int n = 0; n < 2; ++n) _Pragma("unroll") for (int k = 0; k < 2; ++k) dst[n][k] = *(const PG8_LAS bf16x8*)(lds + PG8_SB(b, h) + boff + n * 2048 + k * 1024); } while (0)
; #define PG8_MMA(ai, bj, At, Bt) do { __builtin_amdgcn_s_setprio(1); _Pragma("unroll") for (int m = 0; m < 4; ++m) _Pragma("unroll") for (int n = 0; n < 2; ++n) _Pragma("unroll") for (int k = 0; k < 2; ++k) \
;         acc[ai][bj][m][n] = mma16<Epi::F16>(Bt[n][k], At[m][k], acc[ai][bj][m][n]); __builtin_amdgcn_s_setprio(0); } while (0)
; #define PG8_WAIT_V(n) asm volatile("s_waitcnt vmcnt(" #n ")" ::: "memory")
; #define PG8_WAIT_L(n) asm volatile("s_waitcnt lgkmcnt(" #n ")" ::: "memory")
; #define PG8_BAR __builtin_amdgcn_s_barrier()
; #define PG8_SCHED __builtin_amdgcn_sched_barrier(0)
; template <class Epi, class Sched, bool ALIGN_EPI = false, bool SP2 = false>
; __device__ __forceinline__ void gemm_phase(PG8_LAS unsigned char* lds, const Gemm g, const Sched& S, const Epi& E) {
;     ...
;             PG8_LDB(B0, 0, 0); PG8_LDB(B1, 0, 1); PG8_SCHED; PG8_LDA(At, 0, 0); PG8_STAGE(PG8_SA(1, 1), a1 + hstep, voffA);
;             PG8_WAIT_V(8); PG8_WAIT_L(0); PG8_BAR; PG8_MMA(0, 0, At, B0); PG8_MMA(0, 1, At, B1); PG8_BAR; PG8_SCHED;
;             PG8_LDA(At, 0, 1); PG8_STAGE(PG8_SB(0, 0), b2, voffB); PG8_STAGE(PG8_SB(0, 1), b2 + hstep, voffB); PG8_STAGE(PG8_SA(0, 0), a2, voffA);
.LBB0_152:
	s_add_u32 s10, s8, 0xfffc0080
	s_addc_u32 s11, s9, -1
	s_add_i32 s14, 0, 0x10000
	s_cmp_eq_u32 s52, 12
	s_cselect_b32 s35, s19, s11
	s_cselect_b32 s34, s27, s10
	v_add_u32_e32 v49, s14, v153
	s_cselect_b32 s11, s25, s44
	s_cselect_b32 s10, s36, s37
	s_add_i32 s15, 0, 0x14000
	ds_read_b128 v[142:145], v49
	ds_read_b128 v[146:149], v49 offset:1024
	ds_read_b128 v[158:161], v49 offset:2048
	ds_read_b128 v[162:165], v49 offset:3072
	v_add_u32_e32 v49, s15, v153
	ds_read_b128 v[166:169], v49
	ds_read_b128 v[170:173], v49 offset:1024
	ds_read_b128 v[174:177], v49 offset:2048
	ds_read_b128 v[178:181], v49 offset:3072
	v_lshl_add_u64 v[150:151], s[8:9], 0, v[138:139]
	s_add_i32 m0, s17, 0xc000
	ds_read_b128 v[186:189], v156
	ds_read_b128 v[190:193], v156 offset:1024
	ds_read_b128 v[194:197], v156 offset:2048
	ds_read_b128 v[198:201], v156 offset:3072
	ds_read_b128 v[208:211], v156 offset:4096
	ds_read_b128 v[212:215], v156 offset:5120
	ds_read_b128 v[216:219], v156 offset:6144
	ds_read_b128 v[220:223], v156 offset:7168
	global_load_lds_dwordx4 v[150:151], off
	v_lshl_add_u64 v[150:151], s[8:9], 0, v[140:141]
	s_add_i32 m0, s17, 0xe000
	s_nop 0
	global_load_lds_dwordx4 v[150:151], off
	s_waitcnt vmcnt(8)
	s_waitcnt lgkmcnt(0)
	s_barrier
	s_setprio 1
	s_waitcnt lgkmcnt(0)
	v_mfma_f32_16x16x32_f16 v[126:129], v[142:145], v[186:189], v[126:129]
	v_mfma_f32_16x16x32_f16 v[126:129], v[146:149], v[190:193], v[126:129]
	v_mfma_f32_16x16x32_f16 v[122:125], v[158:161], v[186:189], v[122:125]
	v_mfma_f32_16x16x32_f16 v[122:125], v[162:165], v[190:193], v[122:125]
	v_mfma_f32_16x16x32_f16 v[110:113], v[142:145], v[194:197], v[110:113]
	v_mfma_f32_16x16x32_f16 v[110:113], v[146:149], v[198:201], v[110:113]
	v_mfma_f32_16x16x32_f16 v[106:109], v[158:161], v[194:197], v[106:109]
	v_mfma_f32_16x16x32_f16 v[106:109], v[162:165], v[198:201], v[106:109]
	v_mfma_f32_16x16x32_f16 v[94:97], v[142:145], v[208:211], v[94:97]
	v_mfma_f32_16x16x32_f16 v[94:97], v[146:149], v[212:215], v[94:97]
	v_mfma_f32_16x16x32_f16 v[90:93], v[158:161], v[208:211], v[90:93]
	v_mfma_f32_16x16x32_f16 v[90:93], v[162:165], v[212:215], v[90:93]
	v_mfma_f32_16x16x32_f16 v[78:81], v[142:145], v[216:219], v[78:81]
	v_mfma_f32_16x16x32_f16 v[78:81], v[146:149], v[220:223], v[78:81]
	v_mfma_f32_16x16x32_f16 v[74:77], v[158:161], v[216:219], v[74:77]
	v_mfma_f32_16x16x32_f16 v[74:77], v[162:165], v[220:223], v[74:77]
	s_setprio 0
	s_setprio 1
	v_mfma_f32_16x16x32_f16 v[118:121], v[166:169], v[186:189], v[118:121]
	v_mfma_f32_16x16x32_f16 v[118:121], v[170:173], v[190:193], v[118:121]
	v_mfma_f32_16x16x32_f16 v[114:117], v[174:177], v[186:189], v[114:117]
	v_mfma_f32_16x16x32_f16 v[114:117], v[178:181], v[190:193], v[114:117]
	v_mfma_f32_16x16x32_f16 v[102:105], v[166:169], v[194:197], v[102:105]
	v_mfma_f32_16x16x32_f16 v[102:105], v[170:173], v[198:201], v[102:105]
	v_mfma_f32_16x16x32_f16 v[98:101], v[174:177], v[194:197], v[98:101]
	v_mfma_f32_16x16x32_f16 v[98:101], v[178:181], v[198:201], v[98:101]
	v_mfma_f32_16x16x32_f16 v[86:89], v[166:169], v[208:211], v[86:89]
	v_mfma_f32_16x16x32_f16 v[86:89], v[170:173], v[212:215], v[86:89]
	v_mfma_f32_16x16x32_f16 v[82:85], v[174:177], v[208:211], v[82:85]
	v_mfma_f32_16x16x32_f16 v[82:85], v[178:181], v[212:215], v[82:85]
	v_mfma_f32_16x16x32_f16 v[70:73], v[166:169], v[216:219], v[70:73]
	v_mfma_f32_16x16x32_f16 v[70:73], v[170:173], v[220:223], v[70:73]
	v_mfma_f32_16x16x32_f16 v[66:69], v[174:177], v[216:219], v[66:69]
	v_mfma_f32_16x16x32_f16 v[66:69], v[178:181], v[220:223], v[66:69]
	s_setprio 0
	s_barrier
	s_add_i32 s14, s14, s38
	v_lshl_add_u64 v[150:151], s[10:11], 0, v[132:133]
	s_mov_b32 m0, s14
	ds_read_b128 v[186:189], v156 offset:16384
	ds_read_b128 v[190:193], v156 offset:17408
	ds_read_b128 v[194:197], v156 offset:18432
	ds_read_b128 v[198:201], v156 offset:19456
	ds_read_b128 v[208:211], v156 offset:20480
	ds_read_b128 v[212:215], v156 offset:21504
	ds_read_b128 v[216:219], v156 offset:22528
	ds_read_b128 v[220:223], v156 offset:23552
	global_load_lds_dwordx4 v[150:151], off
	s_add_i32 m0, s14, 0x2000
	s_add_u32 s60, s10, 0x40000
	v_lshl_add_u64 v[182:183], s[10:11], 0, v[136:137]
	s_addc_u32 s61, s11, 0
	s_add_i32 s14, s15, s38
	global_load_lds_dwordx4 v[182:183], off
	v_lshl_add_u64 v[224:225], s[60:61], 0, v[132:133]
	s_mov_b32 m0, s14
	v_lshl_add_u64 v[226:227], s[34:35], 0, v[134:135]
	global_load_lds_dwordx4 v[224:225], off
	v_lshl_add_u64 v[224:225], s[60:61], 0, v[136:137]
	s_add_i32 m0, s14, 0x2000
	s_nop 0
	global_load_lds_dwordx4 v[224:225], off
	v_lshl_add_u64 v[224:225], s[34:35], 0, v[130:131]
	s_mov_b32 m0, s17
	s_nop 0
	global_load_lds_dwordx4 v[224:225], off
	s_mov_b32 m0, s39
	s_nop 0
	global_load_lds_dwordx4 v[226:227], off
	s_waitcnt vmcnt(8)
	s_waitcnt lgkmcnt(0)
	s_barrier
; #define PG8_STAGE(bufoff, gbase, voff) do { _Pragma("unroll") for (int _i = 0; _i < 2; ++_i) \
;         __builtin_amdgcn_global_load_lds((const unsigned*)((const char*)(gbase) + (voff)[_i]), (PG8_LAS unsigned*)(lds + (bufoff) + ldsw + _i * 8192), 16, 0, 0); } while (0)
; #define PG8_LDA(dst, b, h) do { _Pragma("unroll") for (int m = 0; m < 4; ++m) _Pragma("unroll") for (int k = 0; k < 2; ++k) dst[m][k] = *(const PG8_LAS bf16x8*)(lds + PG8_SA(b, h) + aoff + m * 2048 + k * 1024); } while (0)
; #define PG8_LDB(dst, b, h) do { _Pragma("unroll") for (int n = 0; n < 2; ++n) _Pragma("unroll") for (int k = 0; k < 2; ++k) dst[n][k] = *(const PG8_LAS bf16x8*)(lds + PG8_SB(b, h) + boff + n * 2048 + k * 1024); } while (0)
; #define PG8_MMA(ai, bj, At, Bt) do { __builtin_amdgcn_s_setprio(1); _Pragma("unroll") for (int m = 0; m < 4; ++m) _Pragma("unroll") for (int n = 0; n < 2; ++n) _Pragma("unroll") for (int k = 0; k < 2; ++k) \
;         acc[ai][bj][m][n] = mma16<Epi::F16>(Bt[n][k], At[m][k], acc[ai][bj][m][n]); __builtin_amdgcn_s_setprio(0); } while (0)
; #define PG8_WAIT_V(n) asm volatile("s_waitcnt vmcnt(" #n ")" ::: "memory")
; #define PG8_WAIT_L(n) asm volatile("s_waitcnt lgkmcnt(" #n ")" ::: "memory")
; #define PG8_BAR __builtin_amdgcn_s_barrier()
; #define PG8_SCHED __builtin_amdgcn_sched_barrier(0)
; template <class Epi, class Sched, bool ALIGN_EPI = false, bool SP2 = false>
; __device__ __forceinline__ void gemm_phase(PG8_LAS unsigned char* lds, const Gemm g, const Sched& S, const Epi& E) {
;     ...
;             PG8_WAIT_V(8); PG8_WAIT_L(0); PG8_BAR; PG8_MMA(1, 0, At, B0); PG8_MMA(1, 1, At, B1); PG8_BAR; PG8_SCHED;
;             PG8_LDB(B0, 1, 0); PG8_LDB(B1, 1, 1); PG8_SCHED; PG8_LDA(At, 1, 0); PG8_STAGE(PG8_SA(0, 1), a2 + hstep, voffA);
;             PG8_WAIT_V(8); PG8_WAIT_L(0); PG8_BAR; PG8_MMA(0, 0, At, B0); PG8_MMA(0, 1, At, B1); PG8_BAR; PG8_SCHED;
	s_setprio 1
	s_waitcnt lgkmcnt(0)
	v_mfma_f32_16x16x32_f16 v[62:65], v[142:145], v[186:189], v[62:65]
	v_mfma_f32_16x16x32_f16 v[62:65], v[146:149], v[190:193], v[62:65]
	v_mfma_f32_16x16x32_f16 v[58:61], v[158:161], v[186:189], v[58:61]
	v_mfma_f32_16x16x32_f16 v[58:61], v[162:165], v[190:193], v[58:61]
	v_mfma_f32_16x16x32_f16 v[44:47], v[142:145], v[194:197], v[44:47]
	v_mfma_f32_16x16x32_f16 v[44:47], v[146:149], v[198:201], v[44:47]
	v_mfma_f32_16x16x32_f16 v[40:43], v[158:161], v[194:197], v[40:43]
	v_mfma_f32_16x16x32_f16 v[40:43], v[162:165], v[198:201], v[40:43]
	v_mfma_f32_16x16x32_f16 v[28:31], v[142:145], v[208:211], v[28:31]
	v_mfma_f32_16x16x32_f16 v[28:31], v[146:149], v[212:215], v[28:31]
	v_mfma_f32_16x16x32_f16 v[24:27], v[158:161], v[208:211], v[24:27]
	v_mfma_f32_16x16x32_f16 v[24:27], v[162:165], v[212:215], v[24:27]
	v_mfma_f32_16x16x32_f16 v[12:15], v[142:145], v[216:219], v[12:15]
	v_mfma_f32_16x16x32_f16 v[12:15], v[146:149], v[220:223], v[12:15]
	v_mfma_f32_16x16x32_f16 v[8:11], v[158:161], v[216:219], v[8:11]
	v_mfma_f32_16x16x32_f16 v[8:11], v[162:165], v[220:223], v[8:11]
	s_setprio 0
	s_setprio 1
	v_mfma_f32_16x16x32_f16 v[54:57], v[166:169], v[186:189], v[54:57]
	v_mfma_f32_16x16x32_f16 v[54:57], v[170:173], v[190:193], v[54:57]
	v_mfma_f32_16x16x32_f16 v[50:53], v[174:177], v[186:189], v[50:53]
	v_mfma_f32_16x16x32_f16 v[50:53], v[178:181], v[190:193], v[50:53]
	v_mfma_f32_16x16x32_f16 v[36:39], v[166:169], v[194:197], v[36:39]
	v_mfma_f32_16x16x32_f16 v[36:39], v[170:173], v[198:201], v[36:39]
	v_mfma_f32_16x16x32_f16 v[32:35], v[174:177], v[194:197], v[32:35]
	v_mfma_f32_16x16x32_f16 v[32:35], v[178:181], v[198:201], v[32:35]
	v_mfma_f32_16x16x32_f16 v[20:23], v[166:169], v[208:211], v[20:23]
	v_mfma_f32_16x16x32_f16 v[20:23], v[170:173], v[212:215], v[20:23]
	v_mfma_f32_16x16x32_f16 v[16:19], v[174:177], v[208:211], v[16:19]
	v_mfma_f32_16x16x32_f16 v[16:19], v[178:181], v[212:215], v[16:19]
	v_mfma_f32_16x16x32_f16 v[4:7], v[166:169], v[216:219], v[4:7]
	v_mfma_f32_16x16x32_f16 v[4:7], v[170:173], v[220:223], v[4:7]
	v_mfma_f32_16x16x32_f16 v[0:3], v[174:177], v[216:219], v[0:3]
	v_mfma_f32_16x16x32_f16 v[0:3], v[178:181], v[220:223], v[0:3]
	s_setprio 0
	s_barrier
	s_add_i32 s14, 0, 0x18000
	v_add_u32_e32 v49, s14, v153
	s_add_i32 s15, 0, 0x1c000
	ds_read_b128 v[142:145], v49
	ds_read_b128 v[146:149], v49 offset:1024
	ds_read_b128 v[158:161], v49 offset:2048
	ds_read_b128 v[162:165], v49 offset:3072
	v_add_u32_e32 v49, s15, v153
	ds_read_b128 v[166:169], v49
	ds_read_b128 v[170:173], v49 offset:1024
	ds_read_b128 v[174:177], v49 offset:2048
	ds_read_b128 v[178:181], v49 offset:3072
	s_add_u32 s34, s34, 0x40000
	s_addc_u32 s35, s35, 0
	s_mov_b32 m0, s58
	v_lshl_add_u64 v[228:229], s[34:35], 0, v[130:131]
	ds_read_b128 v[186:189], v156 offset:32768
	ds_read_b128 v[190:193], v156 offset:33792
	ds_read_b128 v[194:197], v156 offset:34816
	ds_read_b128 v[198:201], v156 offset:35840
	ds_read_b128 v[208:211], v156 offset:36864
	ds_read_b128 v[212:215], v156 offset:37888
	ds_read_b128 v[216:219], v156 offset:38912
	ds_read_b128 v[220:223], v156 offset:39936
	global_load_lds_dwordx4 v[228:229], off
	v_lshl_add_u64 v[228:229], s[34:35], 0, v[134:135]
	s_mov_b32 m0, s59
	s_nop 0
	global_load_lds_dwordx4 v[228:229], off
	s_waitcnt vmcnt(8)
	s_waitcnt lgkmcnt(0)
	s_barrier
	s_setprio 1
	s_waitcnt lgkmcnt(0)
	v_mfma_f32_16x16x32_f16 v[126:129], v[142:145], v[186:189], v[126:129]
	v_mfma_f32_16x16x32_f16 v[126:129], v[146:149], v[190:193], v[126:129]
	v_mfma_f32_16x16x32_f16 v[122:125], v[158:161], v[186:189], v[122:125]
	v_mfma_f32_16x16x32_f16 v[122:125], v[162:165], v[190:193], v[122:125]
	v_mfma_f32_16x16x32_f16 v[110:113], v[142:145], v[194:197], v[110:113]
	v_mfma_f32_16x16x32_f16 v[110:113], v[146:149], v[198:201], v[110:113]
	v_mfma_f32_16x16x32_f16 v[106:109], v[158:161], v[194:197], v[106:109]
	v_mfma_f32_16x16x32_f16 v[106:109], v[162:165], v[198:201], v[106:109]
	v_mfma_f32_16x16x32_f16 v[94:97], v[142:145], v[208:211], v[94:97]
	v_mfma_f32_16x16x32_f16 v[94:97], v[146:149], v[212:215], v[94:97]
	v_mfma_f32_16x16x32_f16 v[90:93], v[158:161], v[208:211], v[90:93]
	v_mfma_f32_16x16x32_f16 v[90:93], v[162:165], v[212:215], v[90:93]
	v_mfma_f32_16x16x32_f16 v[78:81], v[142:145], v[216:219], v[78:81]
	v_mfma_f32_16x16x32_f16 v[78:81], v[146:149], v[220:223], v[78:81]
	v_mfma_f32_16x16x32_f16 v[74:77], v[158:161], v[216:219], v[74:77]
	v_mfma_f32_16x16x32_f16 v[74:77], v[162:165], v[220:223], v[74:77]
	s_setprio 0
	s_setprio 1
	v_mfma_f32_16x16x32_f16 v[118:121], v[166:169], v[186:189], v[118:121]
	v_mfma_f32_16x16x32_f16 v[118:121], v[170:173], v[190:193], v[118:121]
	v_mfma_f32_16x16x32_f16 v[114:117], v[174:177], v[186:189], v[114:117]
	v_mfma_f32_16x16x32_f16 v[114:117], v[178:181], v[190:193], v[114:117]
	v_mfma_f32_16x16x32_f16 v[102:105], v[166:169], v[194:197], v[102:105]
	v_mfma_f32_16x16x32_f16 v[102:105], v[170:173], v[198:201], v[102:105]
	v_mfma_f32_16x16x32_f16 v[98:101], v[174:177], v[194:197], v[98:101]
	v_mfma_f32_16x16x32_f16 v[98:101], v[178:181], v[198:201], v[98:101]
	v_mfma_f32_16x16x32_f16 v[86:89], v[166:169], v[208:211], v[86:89]
	v_mfma_f32_16x16x32_f16 v[86:89], v[170:173], v[212:215], v[86:89]
	v_mfma_f32_16x16x32_f16 v[82:85], v[174:177], v[208:211], v[82:85]
	v_mfma_f32_16x16x32_f16 v[82:85], v[178:181], v[212:215], v[82:85]
	v_mfma_f32_16x16x32_f16 v[70:73], v[166:169], v[216:219], v[70:73]
	v_mfma_f32_16x16x32_f16 v[70:73], v[170:173], v[220:223], v[70:73]
	v_mfma_f32_16x16x32_f16 v[66:69], v[174:177], v[216:219], v[66:69]
	v_mfma_f32_16x16x32_f16 v[66:69], v[178:181], v[220:223], v[66:69]
	s_setprio 0
	s_barrier
; #define PG8_STAGE(bufoff, gbase, voff) do { _Pragma("unroll") for (int _i = 0; _i < 2; ++_i) \
;         __builtin_amdgcn_global_load_lds((const unsigned*)((const char*)(gbase) + (voff)[_i]), (PG8_LAS unsigned*)(lds + (bufoff) + ldsw + _i * 8192), 16, 0, 0); } while (0)
; #define PG8_LDA(dst, b, h) do { _Pragma("unroll") for (int m = 0; m < 4; ++m) _Pragma("unroll") for (int k = 0; k < 2; ++k) dst[m][k] = *(const PG8_LAS bf16x8*)(lds + PG8_SA(b, h) + aoff + m * 2048 + k * 1024); } while (0)
; #define PG8_MMA(ai, bj, At, Bt) do { __builtin_amdgcn_s_setprio(1); _Pragma("unroll") for (int m = 0; m < 4; ++m) _Pragma("unroll") for (int n = 0; n < 2; ++n) _Pragma("unroll") for (int k = 0; k < 2; ++k) \
;         acc[ai][bj][m][n] = mma16<Epi::F16>(Bt[n][k], At[m][k], acc[ai][bj][m][n]); __builtin_amdgcn_s_setprio(0); } while (0)
; #define PG8_WAIT_V(n) asm volatile("s_waitcnt vmcnt(" #n ")" ::: "memory")
; #define PG8_WAIT_L(n) asm volatile("s_waitcnt lgkmcnt(" #n ")" ::: "memory")
; #define PG8_BAR __builtin_amdgcn_s_barrier()
; #define PG8_SCHED __builtin_amdgcn_sched_barrier(0)
; template <class Epi, class Sched, bool ALIGN_EPI = false, bool SP2 = false>
; __device__ __forceinline__ void gemm_phase(PG8_LAS unsigned char* lds, const Gemm g, const Sched& S, const Epi& E) {
;     ...
;             PG8_LDA(At, 1, 1); PG8_STAGE(PG8_SB(1, 0), b3, voffB); PG8_STAGE(PG8_SB(1, 1), b3 + hstep, voffB); PG8_STAGE(PG8_SA(1, 0), a3, voffA);
;             PG8_WAIT_V(8); PG8_WAIT_L(0); PG8_BAR; PG8_MMA(1, 0, At, B0); PG8_MMA(1, 1, At, B1); PG8_BAR; PG8_SCHED;
	s_add_i32 s14, s14, s38
	v_lshl_add_u64 v[150:151], v[150:151], 0, s[88:89]
	s_mov_b32 m0, s14
	ds_read_b128 v[186:189], v156 offset:49152
	ds_read_b128 v[190:193], v156 offset:50176
	ds_read_b128 v[194:197], v156 offset:51200
	ds_read_b128 v[198:201], v156 offset:52224
	ds_read_b128 v[208:211], v156 offset:53248
	ds_read_b128 v[212:215], v156 offset:54272
	ds_read_b128 v[216:219], v156 offset:55296
	ds_read_b128 v[220:223], v156 offset:56320
	global_load_lds_dwordx4 v[150:151], off
	s_add_i32 m0, s14, 0x2000
	s_add_u32 s10, s10, 0x40080
	v_lshl_add_u64 v[150:151], v[182:183], 0, s[88:89]
	s_addc_u32 s11, s11, 0
	s_add_i32 s14, s15, s38
	global_load_lds_dwordx4 v[150:151], off
	v_lshl_add_u64 v[150:151], s[10:11], 0, v[132:133]
	s_mov_b32 m0, s14
	s_nop 0
	global_load_lds_dwordx4 v[150:151], off
	v_lshl_add_u64 v[150:151], s[10:11], 0, v[136:137]
	s_add_i32 m0, s14, 0x2000
	s_nop 0
	global_load_lds_dwordx4 v[150:151], off
	v_lshl_add_u64 v[150:151], v[224:225], 0, s[88:89]
	s_mov_b32 m0, s62
	s_nop 0
	global_load_lds_dwordx4 v[150:151], off
	v_lshl_add_u64 v[150:151], v[226:227], 0, s[88:89]
	s_mov_b32 m0, s63
	s_nop 0
	global_load_lds_dwordx4 v[150:151], off
	s_waitcnt vmcnt(8)
	s_waitcnt lgkmcnt(0)
	s_barrier
	s_setprio 1
	s_waitcnt lgkmcnt(0)
	v_mfma_f32_16x16x32_f16 v[62:65], v[142:145], v[186:189], v[62:65]
	v_mfma_f32_16x16x32_f16 v[62:65], v[146:149], v[190:193], v[62:65]
	v_mfma_f32_16x16x32_f16 v[58:61], v[158:161], v[186:189], v[58:61]
	v_mfma_f32_16x16x32_f16 v[58:61], v[162:165], v[190:193], v[58:61]
	v_mfma_f32_16x16x32_f16 v[44:47], v[142:145], v[194:197], v[44:47]
	v_mfma_f32_16x16x32_f16 v[44:47], v[146:149], v[198:201], v[44:47]
	v_mfma_f32_16x16x32_f16 v[40:43], v[158:161], v[194:197], v[40:43]
	v_mfma_f32_16x16x32_f16 v[40:43], v[162:165], v[198:201], v[40:43]
	v_mfma_f32_16x16x32_f16 v[28:31], v[142:145], v[208:211], v[28:31]
	v_mfma_f32_16x16x32_f16 v[28:31], v[146:149], v[212:215], v[28:31]
	v_mfma_f32_16x16x32_f16 v[24:27], v[158:161], v[208:211], v[24:27]
	v_mfma_f32_16x16x32_f16 v[24:27], v[162:165], v[212:215], v[24:27]
	v_mfma_f32_16x16x32_f16 v[12:15], v[142:145], v[216:219], v[12:15]
	v_mfma_f32_16x16x32_f16 v[12:15], v[146:149], v[220:223], v[12:15]
	v_mfma_f32_16x16x32_f16 v[8:11], v[158:161], v[216:219], v[8:11]
	v_mfma_f32_16x16x32_f16 v[8:11], v[162:165], v[220:223], v[8:11]
	s_setprio 0
	s_setprio 1
	v_mfma_f32_16x16x32_f16 v[54:57], v[166:169], v[186:189], v[54:57]
	v_mfma_f32_16x16x32_f16 v[54:57], v[170:173], v[190:193], v[54:57]
	v_mfma_f32_16x16x32_f16 v[50:53], v[174:177], v[186:189], v[50:53]
	v_mfma_f32_16x16x32_f16 v[50:53], v[178:181], v[190:193], v[50:53]
	v_mfma_f32_16x16x32_f16 v[36:39], v[166:169], v[194:197], v[36:39]
	v_mfma_f32_16x16x32_f16 v[36:39], v[170:173], v[198:201], v[36:39]
	v_mfma_f32_16x16x32_f16 v[32:35], v[174:177], v[194:197], v[32:35]
	v_mfma_f32_16x16x32_f16 v[32:35], v[178:181], v[198:201], v[32:35]
	v_mfma_f32_16x16x32_f16 v[20:23], v[166:169], v[208:211], v[20:23]
	v_mfma_f32_16x16x32_f16 v[20:23], v[170:173], v[212:215], v[20:23]
	v_mfma_f32_16x16x32_f16 v[16:19], v[174:177], v[208:211], v[16:19]
	v_mfma_f32_16x16x32_f16 v[16:19], v[178:181], v[212:215], v[16:19]
	v_mfma_f32_16x16x32_f16 v[4:7], v[166:169], v[216:219], v[4:7]
	v_mfma_f32_16x16x32_f16 v[4:7], v[170:173], v[220:223], v[4:7]
	v_mfma_f32_16x16x32_f16 v[0:3], v[174:177], v[216:219], v[0:3]
	v_mfma_f32_16x16x32_f16 v[0:3], v[178:181], v[220:223], v[0:3]
	s_setprio 0
	s_barrier
	s_add_i32 s52, s52, 2
	s_add_u32 s8, s8, 0x100
	s_addc_u32 s9, s9, 0
	s_add_u32 s37, s37, 0x100
	s_addc_u32 s44, s44, 0
	s_cmp_gt_u32 s52, 13
	s_cbranch_scc0 .LBB0_152
	s_and_b64 vcc, exec, s[22:23]
	s_cbranch_vccz .LBB0_155
	s_barrier

; #define PG8_STAGE(bufoff, gbase, voff) do { _Pragma("unroll") for (int _i = 0; _i < 2; ++_i) \
;         __builtin_amdgcn_global_load_lds((const unsigned*)((const char*)(gbase) + (voff)[_i]), (PG8_LAS unsigned*)(lds + (bufoff) + ldsw + _i * 8192), 16, 0, 0); } while (0)
; #define PG8_LDA(dst, b, h) do { _Pragma("unroll") for (int m = 0; m < 4; ++m) _Pragma("unroll") for (int k = 0; k < 2; ++k) dst[m][k] = *(const PG8_LAS bf16x8*)(lds + PG8_SA(b, h) + aoff + m * 2048 + k * 1024); } while (0)
; #define PG8_LDB(dst, b, h) do { _Pragma("unroll") for (int n = 0; n < 2; ++n) _Pragma("unroll") for (int k = 0; k < 2; ++k) dst[n][k] = *(const PG8_LAS bf16x8*)(lds + PG8_SB(b, h) + boff + n * 2048 + k * 1024); } while (0)
; #define PG8_MMA(ai, bj, At, Bt) do { __builtin_amdgcn_s_setprio(1); _Pragma("unroll") for (int m = 0; m < 4; ++m) _Pragma("unroll") for (int n = 0; n < 2; ++n) _Pragma("unroll") for (int k = 0; k < 2; ++k) \
;         acc[ai][bj][m][n] = mma16<Epi::F16>(Bt[n][k], At[m][k], acc[ai][bj][m][n]); __builtin_amdgcn_s_setprio(0); } while (0)
; #define PG8_WAIT_V(n) asm volatile("s_waitcnt vmcnt(" #n ")" ::: "memory")
; #define PG8_WAIT_L(n) asm volatile("s_waitcnt lgkmcnt(" #n ")" ::: "memory")
; #define PG8_BAR __builtin_amdgcn_s_barrier()
; #define PG8_SCHED __builtin_amdgcn_sched_barrier(0)
; template <class Epi, class Sched, bool ALIGN_EPI = false, bool SP2 = false>
; __device__ __forceinline__ void gemm_phase(PG8_LAS unsigned char* lds, const Gemm g, const Sched& S, const Epi& E) {
;     ...
;             PG8_LDB(B0, 0, 0); PG8_LDB(B1, 0, 1); PG8_SCHED; PG8_LDA(At, 0, 0); PG8_STAGE(PG8_SA(1, 1), a1 + hstep, voffA);
;             PG8_WAIT_V(8); PG8_WAIT_L(0); PG8_BAR; PG8_MMA(0, 0, At, B0); PG8_MMA(0, 1, At, B1); PG8_BAR; PG8_SCHED;
;             PG8_LDA(At, 0, 1); PG8_STAGE(PG8_SB(0, 0), b2, voffB); PG8_STAGE(PG8_SB(0, 1), b2 + hstep, voffB); PG8_STAGE(PG8_SA(0, 0), a2, voffA);
.LBB0_347:
	s_add_i32 s31, s28, 2
	s_add_u32 s35, s4, 0x80
	s_addc_u32 s29, s5, 0
	s_add_i32 s73, 0, 0x10000
	s_cmp_eq_u32 s65, s28
	s_cselect_b32 s29, s23, s29
	s_cselect_b32 s28, s22, s35
	v_add_u32_e32 v49, s73, v191
	s_cselect_b32 vcc_hi, s25, s30
	s_cselect_b32 vcc_lo, s24, s27
	s_add_i32 s35, 0, 0x14000
	ds_read_b128 v[122:125], v49
	ds_read_b128 v[130:133], v49 offset:1024
	ds_read_b128 v[150:153], v49 offset:2048
	ds_read_b128 v[154:157], v49 offset:3072
	v_add_u32_e32 v49, s35, v191
	ds_read_b128 v[158:161], v49
	ds_read_b128 v[162:165], v49 offset:1024
	ds_read_b128 v[166:169], v49 offset:2048
	ds_read_b128 v[170:173], v49 offset:3072
	v_lshl_add_u64 v[182:183], s[4:5], 0, v[146:147]
	s_add_i32 m0, s59, 0xc000
	ds_read_b128 v[174:177], v192
	ds_read_b128 v[178:181], v192 offset:1024
	ds_read_b128 v[186:189], v192 offset:2048
	ds_read_b128 v[194:197], v192 offset:3072
	ds_read_b128 v[198:201], v192 offset:4096
	ds_read_b128 v[208:211], v192 offset:5120
	ds_read_b128 v[212:215], v192 offset:6144
	ds_read_b128 v[216:219], v192 offset:7168
	global_load_lds_dwordx4 v[182:183], off
	v_lshl_add_u64 v[182:183], s[4:5], 0, v[148:149]
	s_add_i32 m0, s59, 0xe000
	s_nop 0
	global_load_lds_dwordx4 v[182:183], off
	s_waitcnt vmcnt(8)
	s_waitcnt lgkmcnt(0)
	s_barrier
	s_setprio 1
	s_waitcnt lgkmcnt(0)
	v_mfma_f32_16x16x32_bf16 v[134:137], v[122:125], v[174:177], v[134:137]
	v_mfma_f32_16x16x32_bf16 v[134:137], v[130:133], v[178:181], v[134:137]
	v_mfma_f32_16x16x32_bf16 v[126:129], v[150:153], v[174:177], v[126:129]
	v_mfma_f32_16x16x32_bf16 v[126:129], v[154:157], v[178:181], v[126:129]
	v_mfma_f32_16x16x32_bf16 v[110:113], v[122:125], v[186:189], v[110:113]
	v_mfma_f32_16x16x32_bf16 v[110:113], v[130:133], v[194:197], v[110:113]
	v_mfma_f32_16x16x32_bf16 v[106:109], v[150:153], v[186:189], v[106:109]
	v_mfma_f32_16x16x32_bf16 v[106:109], v[154:157], v[194:197], v[106:109]
	v_mfma_f32_16x16x32_bf16 v[94:97], v[122:125], v[198:201], v[94:97]
	v_mfma_f32_16x16x32_bf16 v[94:97], v[130:133], v[208:211], v[94:97]
	v_mfma_f32_16x16x32_bf16 v[90:93], v[150:153], v[198:201], v[90:93]
	v_mfma_f32_16x16x32_bf16 v[90:93], v[154:157], v[208:211], v[90:93]
	v_mfma_f32_16x16x32_bf16 v[78:81], v[122:125], v[212:215], v[78:81]
	v_mfma_f32_16x16x32_bf16 v[78:81], v[130:133], v[216:219], v[78:81]
	v_mfma_f32_16x16x32_bf16 v[74:77], v[150:153], v[212:215], v[74:77]
	v_mfma_f32_16x16x32_bf16 v[74:77], v[154:157], v[216:219], v[74:77]
	s_setprio 0
	s_setprio 1
	v_mfma_f32_16x16x32_bf16 v[118:121], v[158:161], v[174:177], v[118:121]
	v_mfma_f32_16x16x32_bf16 v[118:121], v[162:165], v[178:181], v[118:121]
	v_mfma_f32_16x16x32_bf16 v[114:117], v[166:169], v[174:177], v[114:117]
	v_mfma_f32_16x16x32_bf16 v[114:117], v[170:173], v[178:181], v[114:117]
	v_mfma_f32_16x16x32_bf16 v[102:105], v[158:161], v[186:189], v[102:105]
	v_mfma_f32_16x16x32_bf16 v[102:105], v[162:165], v[194:197], v[102:105]
	v_mfma_f32_16x16x32_bf16 v[98:101], v[166:169], v[186:189], v[98:101]
	v_mfma_f32_16x16x32_bf16 v[98:101], v[170:173], v[194:197], v[98:101]
	v_mfma_f32_16x16x32_bf16 v[86:89], v[158:161], v[198:201], v[86:89]
	v_mfma_f32_16x16x32_bf16 v[86:89], v[162:165], v[208:211], v[86:89]
	v_mfma_f32_16x16x32_bf16 v[82:85], v[166:169], v[198:201], v[82:85]
	v_mfma_f32_16x16x32_bf16 v[82:85], v[170:173], v[208:211], v[82:85]
	v_mfma_f32_16x16x32_bf16 v[70:73], v[158:161], v[212:215], v[70:73]
	v_mfma_f32_16x16x32_bf16 v[70:73], v[162:165], v[216:219], v[70:73]
	v_mfma_f32_16x16x32_bf16 v[66:69], v[166:169], v[212:215], v[66:69]
	v_mfma_f32_16x16x32_bf16 v[66:69], v[170:173], v[216:219], v[66:69]
	s_setprio 0
	s_barrier
	s_add_i32 s73, s73, s58
	v_lshl_add_u64 v[182:183], vcc, 0, v[140:141]
	s_mov_b32 m0, s73
	ds_read_b128 v[174:177], v192 offset:16384
	ds_read_b128 v[178:181], v192 offset:17408
	ds_read_b128 v[186:189], v192 offset:18432
	ds_read_b128 v[194:197], v192 offset:19456
	ds_read_b128 v[198:201], v192 offset:20480
	ds_read_b128 v[208:211], v192 offset:21504
	ds_read_b128 v[212:215], v192 offset:22528
	ds_read_b128 v[216:219], v192 offset:23552
	global_load_lds_dwordx4 v[182:183], off
	s_add_i32 m0, s73, 0x2000
	v_lshl_add_u64 v[220:221], vcc, 0, v[144:145]
	s_add_u32 vcc_lo, vcc_lo, s44
	s_addc_u32 vcc_hi, vcc_hi, 0
	s_add_i32 s35, s35, s58
	global_load_lds_dwordx4 v[220:221], off
	v_lshl_add_u64 v[222:223], vcc, 0, v[140:141]
	s_mov_b32 m0, s35
	v_lshl_add_u64 v[224:225], vcc, 0, v[144:145]
	global_load_lds_dwordx4 v[222:223], off
	s_add_i32 m0, s35, 0x2000
	v_lshl_add_u64 v[226:227], s[28:29], 0, v[138:139]
	global_load_lds_dwordx4 v[224:225], off
	s_mov_b32 m0, s59
	v_lshl_add_u64 v[228:229], s[28:29], 0, v[142:143]
	global_load_lds_dwordx4 v[226:227], off
	s_mov_b32 m0, s62
	s_nop 0
	global_load_lds_dwordx4 v[228:229], off
	s_waitcnt vmcnt(8)
	s_waitcnt lgkmcnt(0)
	s_barrier
; #define PG8_STAGE(bufoff, gbase, voff) do { _Pragma("unroll") for (int _i = 0; _i < 2; ++_i) \
;         __builtin_amdgcn_global_load_lds((const unsigned*)((const char*)(gbase) + (voff)[_i]), (PG8_LAS unsigned*)(lds + (bufoff) + ldsw + _i * 8192), 16, 0, 0); } while (0)
; #define PG8_LDA(dst, b, h) do { _Pragma("unroll") for (int m = 0; m < 4; ++m) _Pragma("unroll") for (int k = 0; k < 2; ++k) dst[m][k] = *(const PG8_LAS bf16x8*)(lds + PG8_SA(b, h) + aoff + m * 2048 + k * 1024); } while (0)
; #define PG8_LDB(dst, b, h) do { _Pragma("unroll") for (int n = 0; n < 2; ++n) _Pragma("unroll") for (int k = 0; k < 2; ++k) dst[n][k] = *(const PG8_LAS bf16x8*)(lds + PG8_SB(b, h) + boff + n * 2048 + k * 1024); } while (0)
; #define PG8_MMA(ai, bj, At, Bt) do { __builtin_amdgcn_s_setprio(1); _Pragma("unroll") for (int m = 0; m < 4; ++m) _Pragma("unroll") for (int n = 0; n < 2; ++n) _Pragma("unroll") for (int k = 0; k < 2; ++k) \
;         acc[ai][bj][m][n] = mma16<Epi::F16>(Bt[n][k], At[m][k], acc[ai][bj][m][n]); __builtin_amdgcn_s_setprio(0); } while (0)
; #define PG8_WAIT_V(n) asm volatile("s_waitcnt vmcnt(" #n ")" ::: "memory")
; #define PG8_WAIT_L(n) asm volatile("s_waitcnt lgkmcnt(" #n ")" ::: "memory")
; #define PG8_BAR __builtin_amdgcn_s_barrier()
; #define PG8_SCHED __builtin_amdgcn_sched_barrier(0)
; template <class Epi, class Sched, bool ALIGN_EPI = false, bool SP2 = false>
; __device__ __forceinline__ void gemm_phase(PG8_LAS unsigned char* lds, const Gemm g, const Sched& S, const Epi& E) {
;     ...
;             PG8_WAIT_V(8); PG8_WAIT_L(0); PG8_BAR; PG8_MMA(1, 0, At, B0); PG8_MMA(1, 1, At, B1); PG8_BAR; PG8_SCHED;
;             PG8_LDB(B0, 1, 0); PG8_LDB(B1, 1, 1); PG8_SCHED; PG8_LDA(At, 1, 0); PG8_STAGE(PG8_SA(0, 1), a2 + hstep, voffA);
;             PG8_WAIT_V(8); PG8_WAIT_L(0); PG8_BAR; PG8_MMA(0, 0, At, B0); PG8_MMA(0, 1, At, B1); PG8_BAR; PG8_SCHED;
	s_setprio 1
	s_waitcnt lgkmcnt(0)
	v_mfma_f32_16x16x32_bf16 v[62:65], v[122:125], v[174:177], v[62:65]
	v_mfma_f32_16x16x32_bf16 v[62:65], v[130:133], v[178:181], v[62:65]
	v_mfma_f32_16x16x32_bf16 v[58:61], v[150:153], v[174:177], v[58:61]
	v_mfma_f32_16x16x32_bf16 v[58:61], v[154:157], v[178:181], v[58:61]
	v_mfma_f32_16x16x32_bf16 v[44:47], v[122:125], v[186:189], v[44:47]
	v_mfma_f32_16x16x32_bf16 v[44:47], v[130:133], v[194:197], v[44:47]
	v_mfma_f32_16x16x32_bf16 v[40:43], v[150:153], v[186:189], v[40:43]
	v_mfma_f32_16x16x32_bf16 v[40:43], v[154:157], v[194:197], v[40:43]
	v_mfma_f32_16x16x32_bf16 v[28:31], v[122:125], v[198:201], v[28:31]
	v_mfma_f32_16x16x32_bf16 v[28:31], v[130:133], v[208:211], v[28:31]
	v_mfma_f32_16x16x32_bf16 v[24:27], v[150:153], v[198:201], v[24:27]
	v_mfma_f32_16x16x32_bf16 v[24:27], v[154:157], v[208:211], v[24:27]
	v_mfma_f32_16x16x32_bf16 v[12:15], v[122:125], v[212:215], v[12:15]
	v_mfma_f32_16x16x32_bf16 v[12:15], v[130:133], v[216:219], v[12:15]
	v_mfma_f32_16x16x32_bf16 v[8:11], v[150:153], v[212:215], v[8:11]
	v_mfma_f32_16x16x32_bf16 v[8:11], v[154:157], v[216:219], v[8:11]
	s_setprio 0
	s_setprio 1
	v_mfma_f32_16x16x32_bf16 v[54:57], v[158:161], v[174:177], v[54:57]
	v_mfma_f32_16x16x32_bf16 v[54:57], v[162:165], v[178:181], v[54:57]
	v_mfma_f32_16x16x32_bf16 v[50:53], v[166:169], v[174:177], v[50:53]
	v_mfma_f32_16x16x32_bf16 v[50:53], v[170:173], v[178:181], v[50:53]
	v_mfma_f32_16x16x32_bf16 v[36:39], v[158:161], v[186:189], v[36:39]
	v_mfma_f32_16x16x32_bf16 v[36:39], v[162:165], v[194:197], v[36:39]
	v_mfma_f32_16x16x32_bf16 v[32:35], v[166:169], v[186:189], v[32:35]
	v_mfma_f32_16x16x32_bf16 v[32:35], v[170:173], v[194:197], v[32:35]
	v_mfma_f32_16x16x32_bf16 v[20:23], v[158:161], v[198:201], v[20:23]
	v_mfma_f32_16x16x32_bf16 v[20:23], v[162:165], v[208:211], v[20:23]
	v_mfma_f32_16x16x32_bf16 v[16:19], v[166:169], v[198:201], v[16:19]
	v_mfma_f32_16x16x32_bf16 v[16:19], v[170:173], v[208:211], v[16:19]
	v_mfma_f32_16x16x32_bf16 v[4:7], v[158:161], v[212:215], v[4:7]
	v_mfma_f32_16x16x32_bf16 v[4:7], v[162:165], v[216:219], v[4:7]
	v_mfma_f32_16x16x32_bf16 v[0:3], v[166:169], v[212:215], v[0:3]
	v_mfma_f32_16x16x32_bf16 v[0:3], v[170:173], v[216:219], v[0:3]
	s_setprio 0
	s_barrier
	s_add_i32 s35, 0, 0x18000
	v_add_u32_e32 v49, s35, v191
	s_add_i32 s73, 0, 0x1c000
	ds_read_b128 v[122:125], v49
	ds_read_b128 v[130:133], v49 offset:1024
	ds_read_b128 v[150:153], v49 offset:2048
	ds_read_b128 v[154:157], v49 offset:3072
	v_add_u32_e32 v49, s73, v191
	ds_read_b128 v[158:161], v49
	ds_read_b128 v[162:165], v49 offset:1024
	ds_read_b128 v[166:169], v49 offset:2048
	ds_read_b128 v[170:173], v49 offset:3072
	s_add_u32 s28, s28, s44
	s_addc_u32 s29, s29, 0
	s_mov_b32 m0, s63
	v_lshl_add_u64 v[230:231], s[28:29], 0, v[138:139]
	ds_read_b128 v[174:177], v192 offset:32768
	ds_read_b128 v[178:181], v192 offset:33792
	ds_read_b128 v[186:189], v192 offset:34816
	ds_read_b128 v[194:197], v192 offset:35840
	ds_read_b128 v[198:201], v192 offset:36864
	ds_read_b128 v[208:211], v192 offset:37888
	ds_read_b128 v[212:215], v192 offset:38912
	ds_read_b128 v[216:219], v192 offset:39936
	global_load_lds_dwordx4 v[230:231], off
	v_lshl_add_u64 v[230:231], s[28:29], 0, v[142:143]
	s_mov_b32 m0, s64
	s_nop 0
	global_load_lds_dwordx4 v[230:231], off
	s_waitcnt vmcnt(8)
	s_waitcnt lgkmcnt(0)
	s_barrier
	s_setprio 1
	s_waitcnt lgkmcnt(0)
	v_mfma_f32_16x16x32_bf16 v[134:137], v[122:125], v[174:177], v[134:137]
	v_mfma_f32_16x16x32_bf16 v[134:137], v[130:133], v[178:181], v[134:137]
	v_mfma_f32_16x16x32_bf16 v[126:129], v[150:153], v[174:177], v[126:129]
	v_mfma_f32_16x16x32_bf16 v[126:129], v[154:157], v[178:181], v[126:129]
	v_mfma_f32_16x16x32_bf16 v[110:113], v[122:125], v[186:189], v[110:113]
	v_mfma_f32_16x16x32_bf16 v[110:113], v[130:133], v[194:197], v[110:113]
	v_mfma_f32_16x16x32_bf16 v[106:109], v[150:153], v[186:189], v[106:109]
	v_mfma_f32_16x16x32_bf16 v[106:109], v[154:157], v[194:197], v[106:109]
	v_mfma_f32_16x16x32_bf16 v[94:97], v[122:125], v[198:201], v[94:97]
	v_mfma_f32_16x16x32_bf16 v[94:97], v[130:133], v[208:211], v[94:97]
	v_mfma_f32_16x16x32_bf16 v[90:93], v[150:153], v[198:201], v[90:93]
	v_mfma_f32_16x16x32_bf16 v[90:93], v[154:157], v[208:211], v[90:93]
	v_mfma_f32_16x16x32_bf16 v[78:81], v[122:125], v[212:215], v[78:81]
	v_mfma_f32_16x16x32_bf16 v[78:81], v[130:133], v[216:219], v[78:81]
	v_mfma_f32_16x16x32_bf16 v[74:77], v[150:153], v[212:215], v[74:77]
	v_mfma_f32_16x16x32_bf16 v[74:77], v[154:157], v[216:219], v[74:77]
	s_setprio 0
	s_setprio 1
	v_mfma_f32_16x16x32_bf16 v[118:121], v[158:161], v[174:177], v[118:121]
	v_mfma_f32_16x16x32_bf16 v[118:121], v[162:165], v[178:181], v[118:121]
	v_mfma_f32_16x16x32_bf16 v[114:117], v[166:169], v[174:177], v[114:117]
	v_mfma_f32_16x16x32_bf16 v[114:117], v[170:173], v[178:181], v[114:117]
	v_mfma_f32_16x16x32_bf16 v[102:105], v[158:161], v[186:189], v[102:105]
	v_mfma_f32_16x16x32_bf16 v[102:105], v[162:165], v[194:197], v[102:105]
	v_mfma_f32_16x16x32_bf16 v[98:101], v[166:169], v[186:189], v[98:101]
	v_mfma_f32_16x16x32_bf16 v[98:101], v[170:173], v[194:197], v[98:101]
	v_mfma_f32_16x16x32_bf16 v[86:89], v[158:161], v[198:201], v[86:89]
	v_mfma_f32_16x16x32_bf16 v[86:89], v[162:165], v[208:211], v[86:89]
	v_mfma_f32_16x16x32_bf16 v[82:85], v[166:169], v[198:201], v[82:85]
	v_mfma_f32_16x16x32_bf16 v[82:85], v[170:173], v[208:211], v[82:85]
	v_mfma_f32_16x16x32_bf16 v[70:73], v[158:161], v[212:215], v[70:73]
	v_mfma_f32_16x16x32_bf16 v[70:73], v[162:165], v[216:219], v[70:73]
	v_mfma_f32_16x16x32_bf16 v[66:69], v[166:169], v[212:215], v[66:69]
	v_mfma_f32_16x16x32_bf16 v[66:69], v[170:173], v[216:219], v[66:69]
	s_setprio 0
	s_barrier
; #define PG8_STAGE(bufoff, gbase, voff) do { _Pragma("unroll") for (int _i = 0; _i < 2; ++_i) \
;         __builtin_amdgcn_global_load_lds((const unsigned*)((const char*)(gbase) + (voff)[_i]), (PG8_LAS unsigned*)(lds + (bufoff) + ldsw + _i * 8192), 16, 0, 0); } while (0)
; #define PG8_LDA(dst, b, h) do { _Pragma("unroll") for (int m = 0; m < 4; ++m) _Pragma("unroll") for (int k = 0; k < 2; ++k) dst[m][k] = *(const PG8_LAS bf16x8*)(lds + PG8_SA(b, h) + aoff + m * 2048 + k * 1024); } while (0)
; #define PG8_MMA(ai, bj, At, Bt) do { __builtin_amdgcn_s_setprio(1); _Pragma("unroll") for (int m = 0; m < 4; ++m) _Pragma("unroll") for (int n = 0; n < 2; ++n) _Pragma("unroll") for (int k = 0; k < 2; ++k) \
;         acc[ai][bj][m][n] = mma16<Epi::F16>(Bt[n][k], At[m][k], acc[ai][bj][m][n]); __builtin_amdgcn_s_setprio(0); } while (0)
; #define PG8_WAIT_V(n) asm volatile("s_waitcnt vmcnt(" #n ")" ::: "memory")
; #define PG8_WAIT_L(n) asm volatile("s_waitcnt lgkmcnt(" #n ")" ::: "memory")
; #define PG8_BAR __builtin_amdgcn_s_barrier()
; #define PG8_SCHED __builtin_amdgcn_sched_barrier(0)
; template <class Epi, class Sched, bool ALIGN_EPI = false, bool SP2 = false>
; __device__ __forceinline__ void gemm_phase(PG8_LAS unsigned char* lds, const Gemm g, const Sched& S, const Epi& E) {
;     ...
;             PG8_LDA(At, 1, 1); PG8_STAGE(PG8_SB(1, 0), b3, voffB); PG8_STAGE(PG8_SB(1, 1), b3 + hstep, voffB); PG8_STAGE(PG8_SA(1, 0), a3, voffA);
;             PG8_WAIT_V(8); PG8_WAIT_L(0); PG8_BAR; PG8_MMA(1, 0, At, B0); PG8_MMA(1, 1, At, B1); PG8_BAR; PG8_SCHED;
	s_add_i32 s28, s35, s58
	v_lshl_add_u64 v[182:183], v[182:183], 0, s[88:89]
	s_mov_b32 m0, s28
	ds_read_b128 v[174:177], v192 offset:49152
	ds_read_b128 v[178:181], v192 offset:50176
	ds_read_b128 v[186:189], v192 offset:51200
	ds_read_b128 v[194:197], v192 offset:52224
	ds_read_b128 v[198:201], v192 offset:53248
	ds_read_b128 v[208:211], v192 offset:54272
	ds_read_b128 v[212:215], v192 offset:55296
	ds_read_b128 v[216:219], v192 offset:56320
	global_load_lds_dwordx4 v[182:183], off
	v_lshl_add_u64 v[182:183], v[220:221], 0, s[88:89]
	s_add_i32 m0, s28, 0x2000
	s_add_i32 s28, s73, s58
	global_load_lds_dwordx4 v[182:183], off
	v_lshl_add_u64 v[182:183], v[222:223], 0, s[88:89]
	s_mov_b32 m0, s28
	s_nop 0
	global_load_lds_dwordx4 v[182:183], off
	v_lshl_add_u64 v[182:183], v[224:225], 0, s[88:89]
	s_add_i32 m0, s28, 0x2000
	s_nop 0
	global_load_lds_dwordx4 v[182:183], off
	v_lshl_add_u64 v[182:183], v[226:227], 0, s[88:89]
	s_mov_b32 m0, s98
	s_nop 0
	global_load_lds_dwordx4 v[182:183], off
	v_lshl_add_u64 v[182:183], v[228:229], 0, s[88:89]
	s_mov_b32 m0, s99
	s_nop 0
	global_load_lds_dwordx4 v[182:183], off
	s_waitcnt vmcnt(8)
	s_waitcnt lgkmcnt(0)
	s_barrier
	s_setprio 1
	s_waitcnt lgkmcnt(0)
	v_mfma_f32_16x16x32_bf16 v[62:65], v[122:125], v[174:177], v[62:65]
	v_mfma_f32_16x16x32_bf16 v[62:65], v[130:133], v[178:181], v[62:65]
	v_mfma_f32_16x16x32_bf16 v[58:61], v[150:153], v[174:177], v[58:61]
	v_mfma_f32_16x16x32_bf16 v[58:61], v[154:157], v[178:181], v[58:61]
	v_mfma_f32_16x16x32_bf16 v[44:47], v[122:125], v[186:189], v[44:47]
	v_mfma_f32_16x16x32_bf16 v[44:47], v[130:133], v[194:197], v[44:47]
	v_mfma_f32_16x16x32_bf16 v[40:43], v[150:153], v[186:189], v[40:43]
	v_mfma_f32_16x16x32_bf16 v[40:43], v[154:157], v[194:197], v[40:43]
	v_mfma_f32_16x16x32_bf16 v[28:31], v[122:125], v[198:201], v[28:31]
	v_mfma_f32_16x16x32_bf16 v[28:31], v[130:133], v[208:211], v[28:31]
	v_mfma_f32_16x16x32_bf16 v[24:27], v[150:153], v[198:201], v[24:27]
	v_mfma_f32_16x16x32_bf16 v[24:27], v[154:157], v[208:211], v[24:27]
	v_mfma_f32_16x16x32_bf16 v[12:15], v[122:125], v[212:215], v[12:15]
	v_mfma_f32_16x16x32_bf16 v[12:15], v[130:133], v[216:219], v[12:15]
	v_mfma_f32_16x16x32_bf16 v[8:11], v[150:153], v[212:215], v[8:11]
	v_mfma_f32_16x16x32_bf16 v[8:11], v[154:157], v[216:219], v[8:11]
	s_setprio 0
	s_setprio 1
	v_mfma_f32_16x16x32_bf16 v[54:57], v[158:161], v[174:177], v[54:57]
	v_mfma_f32_16x16x32_bf16 v[54:57], v[162:165], v[178:181], v[54:57]
	v_mfma_f32_16x16x32_bf16 v[50:53], v[166:169], v[174:177], v[50:53]
	v_mfma_f32_16x16x32_bf16 v[50:53], v[170:173], v[178:181], v[50:53]
	v_mfma_f32_16x16x32_bf16 v[36:39], v[158:161], v[186:189], v[36:39]
	v_mfma_f32_16x16x32_bf16 v[36:39], v[162:165], v[194:197], v[36:39]
	v_mfma_f32_16x16x32_bf16 v[32:35], v[166:169], v[186:189], v[32:35]
	v_mfma_f32_16x16x32_bf16 v[32:35], v[170:173], v[194:197], v[32:35]
	v_mfma_f32_16x16x32_bf16 v[20:23], v[158:161], v[198:201], v[20:23]
	v_mfma_f32_16x16x32_bf16 v[20:23], v[162:165], v[208:211], v[20:23]
	v_mfma_f32_16x16x32_bf16 v[16:19], v[166:169], v[198:201], v[16:19]
	v_mfma_f32_16x16x32_bf16 v[16:19], v[170:173], v[208:211], v[16:19]
	v_mfma_f32_16x16x32_bf16 v[4:7], v[158:161], v[212:215], v[4:7]
	v_mfma_f32_16x16x32_bf16 v[4:7], v[162:165], v[216:219], v[4:7]
	v_mfma_f32_16x16x32_bf16 v[0:3], v[166:169], v[212:215], v[0:3]
	v_mfma_f32_16x16x32_bf16 v[0:3], v[170:173], v[216:219], v[0:3]
	s_setprio 0
	s_barrier
	s_add_u32 s4, s4, 0x100
	s_addc_u32 s5, s5, 0
	s_add_u32 s27, s27, 0x100
	s_addc_u32 s30, s30, 0
	s_cmp_ge_u32 s31, s76
	s_mov_b32 s28, s31
	s_cbranch_scc0 .LBB0_347
	s_and_b64 vcc, exec, s[16:17]
	s_cbranch_vccz .LBB0_350
	s_barrier
